# P3 L2 row warm-up one ticket round ahead (junk LDS at 0x20200) stacked on the LDS-staged cmp task
# baseline (speedup 1.0000x reference)
; DI size_t sc_rowoff(int b, int t) { const int c = t >> 6; return (size_t)b * SC_PB + (size_t)4096 * (c * (c + 1) / 2) + (size_t)(t & 63) * (64 * (c + 1)); }
; DI void select_row(const float* SC, unsigned* dmask, int b, int t, int lane) {
;     unsigned* dm = dmask + ((size_t)b * SEQ + t) * 64;
;     const int nvalid = t + 1;
;     if (nvalid <= 256) {
;         const int w = lane;
;         const int lo = 32 * w; unsigned bits = 0u;
;         if (lo + 31 <= t) bits = 0xffffffffu; else if (lo <= t) bits = (2u << (t - lo)) - 1u;
;         dm[w] = bits; return;
;     }
;     const int nch = (nvalid + 255) >> 8;
;     const float* srow = SC + sc_rowoff(b, t) + 4 * lane;
.Lsel_pf_done:
	s_mov_b32 s99, 0x80000000
	v_mov_b32_e32 v121, v43
	v_lshl_add_u64 v[10:11], s[8:9], 0, v[120:121]
	s_cmpk_lt_u32 s65, 0x180
	s_cbranch_scc1 .Lsel_l2pf_skip
	s_add_i32 s8, s65, 0xffffff80
	s_lshr_b32 s9, s8, 6
	s_add_i32 s10, s9, 1
	s_mul_i32 s9, s9, s10
	s_lshl_b32 s9, s9, 13
	s_and_b32 s8, s8, 63
	s_mul_i32 s8, s8, s10
	s_lshl_b32 s8, s8, 8
	s_add_i32 s8, s8, s9
	s_and_b32 s14, s92, 8
	s_and_b32 s98, s47, 7
	s_or_b32 s14, s14, s98
	s_mul_i32 s14, s14, 0x840000
	s_add_i32 s8, s8, s14
	s_add_u32 s8, s44, s8
	s_addc_u32 s9, s45, 0
	s_lshl_b32 s10, s10, 1
	s_lshl_b64 s[10:11], 1, s10
	s_add_u32 s10, s10, -1
	s_addc_u32 s11, s11, -1
	v_lshlrev_b32_e32 v189, 3, v120
	s_mov_b32 m0, 0x20200
	s_mov_b64 vcc, exec
	s_mov_b64 exec, s[10:11]
	s_nop 1
	global_load_lds_dword v189, s[8:9]
	s_mov_b64 exec, vcc
